# k27: loop-edge edit (guide 7.11) on attention steady loops: post-barrier SALU bookkeeping moved in front of the per-tile barriers; '+0' row-sum add folded; on top of tightened scan DMA block
# speedup vs baseline: 1.0118x; 1.0067x over previous
.LBB0_1332:
	s_lshl_b32 s4, s4, 1
	v_add_u32_e32 v243, s4, v239
	ds_read_b64_tr_b16 v[208:209], v243 offset:24576
	ds_read_b64_tr_b16 v[210:211], v243 offset:25088
	s_waitcnt lgkmcnt(9)
	v_mfma_f32_32x32x16_bf16 v[128:143], v[204:207], v[172:175], v[64:79]
	v_add_f32_e32 v112, v96, v97
	v_add_f32_e32 v112, v98, v112
	v_add_f32_e32 v112, v99, v112
	v_add_f32_e32 v112, v100, v112
	v_add_f32_e32 v112, v101, v112
	v_cvt_pk_bf16_f32 v164, v96, v97
	v_cvt_pk_bf16_f32 v165, v98, v99
	ds_read_b64_tr_b16 v[96:97], v243 offset:28672
	ds_read_b64_tr_b16 v[98:99], v243 offset:29184
	v_add_f32_e32 v112, v102, v112
	v_add_f32_e32 v112, v103, v112
	v_add_f32_e32 v112, v104, v112
	v_add_f32_e32 v144, v105, v112
	s_waitcnt lgkmcnt(10)
	v_mfma_f32_32x32x16_bf16 v[112:127], v[200:203], v[172:175], v[64:79]
	v_cvt_pk_bf16_f32 v166, v100, v101
	v_cvt_pk_bf16_f32 v167, v102, v103
	ds_read_b64_tr_b16 v[100:101], v243 offset:25600
	ds_read_b64_tr_b16 v[102:103], v243 offset:26112
	s_waitcnt lgkmcnt(11)
	v_mfma_f32_32x32x16_bf16 v[128:143], v[196:199], v[168:171], v[128:143]
	v_add_f32_e32 v144, v106, v144
	v_add_f32_e32 v144, v107, v144
	v_add_f32_e32 v144, v108, v144
	v_add_f32_e32 v144, v109, v144
	v_cvt_pk_bf16_f32 v156, v104, v105
	v_cvt_pk_bf16_f32 v157, v106, v107
	ds_read_b64_tr_b16 v[104:105], v243 offset:29696
	ds_read_b64_tr_b16 v[106:107], v243 offset:30208
	s_waitcnt lgkmcnt(12)
	v_mfma_f32_32x32x16_bf16 v[112:127], v[192:195], v[168:171], v[112:127]
	v_add_f32_e32 v144, v110, v144
	v_add_f32_e32 v144, v111, v144
	v_add_f32_e32 v144, v80, v144
	v_add_f32_e32 v144, v81, v144
	v_cvt_pk_bf16_f32 v158, v108, v109
	v_cvt_pk_bf16_f32 v159, v110, v111
	ds_read_b64_tr_b16 v[108:109], v243 offset:26624
	ds_read_b64_tr_b16 v[110:111], v243 offset:27136
	s_waitcnt lgkmcnt(13)
	v_mfma_f32_32x32x16_bf16 v[128:143], v[188:191], v[160:163], v[128:143]
	v_add_f32_e32 v144, v82, v144
	v_add_f32_e32 v144, v83, v144
	v_add_f32_e32 v144, v84, v144
	v_add_f32_e32 v144, v85, v144
	v_cvt_pk_bf16_f32 v148, v80, v81
	v_cvt_pk_bf16_f32 v149, v82, v83
	ds_read_b64_tr_b16 v[80:81], v243 offset:30720
	ds_read_b64_tr_b16 v[82:83], v243 offset:31232
	s_waitcnt lgkmcnt(14)
	v_mfma_f32_32x32x16_bf16 v[112:127], v[184:187], v[160:163], v[112:127]
	v_add_f32_e32 v144, v86, v144
	v_add_f32_e32 v144, v87, v144
	v_add_f32_e32 v144, v88, v144
	v_add_f32_e32 v144, v89, v144
	v_cvt_pk_bf16_f32 v150, v84, v85
	v_cvt_pk_bf16_f32 v151, v86, v87
	ds_read_b64_tr_b16 v[84:85], v243 offset:27648
	ds_read_b64_tr_b16 v[86:87], v243 offset:28160
	s_waitcnt lgkmcnt(14)
	v_mfma_f32_32x32x16_bf16 v[128:143], v[180:183], v[152:155], v[128:143]
	v_add_f32_e32 v144, v90, v144
	v_add_f32_e32 v144, v91, v144
	v_add_f32_e32 v144, v92, v144
	v_add_f32_e32 v184, v93, v144
	v_cvt_pk_bf16_f32 v144, v88, v89
	v_cvt_pk_bf16_f32 v145, v90, v91
	ds_read_b64_tr_b16 v[88:89], v243 offset:31744
	ds_read_b64_tr_b16 v[90:91], v243 offset:32256
	v_mfma_f32_32x32x16_bf16 v[112:127], v[176:179], v[152:155], v[112:127]
	v_add_f32_e32 v146, v94, v184
	v_add_f32_e32 v146, v95, v146
	v_add_f32_e32 v241, v241, v146
	v_cvt_pk_bf16_f32 v146, v92, v93
	v_cvt_pk_bf16_f32 v147, v94, v95
	s_add_i32 s4, s11, s76
	s_mov_b32 m0, s4
	s_nop 0
	global_load_lds_dwordx4 v248, s[98:99]
	s_lshl_b32 s4, s38, 1
	s_add_i32 s4, s4, s77
	s_mov_b32 m0, s4
	s_nop 0
	global_load_lds_dwordx4 v250, s[100:101]
	s_addk_i32 s4, 0x2000
	s_mov_b32 m0, s4
	s_nop 0
	global_load_lds_dwordx4 v252, s[100:101]
	v_max_f32_e32 v92, v128, v129
	v_max3_f32 v93, v130, v131, v113
	v_max3_f32 v92, v92, v112, v114
	v_max3_f32 v92, v92, v115, v132
	v_max3_f32 v93, v93, v134, v135
	v_max3_f32 v92, v92, v133, v116
	v_max3_f32 v93, v93, v118, v119
	v_max3_f32 v92, v92, v117, v136
	v_max3_f32 v93, v93, v138, v139
	v_max3_f32 v92, v92, v137, v120
	v_max3_f32 v93, v93, v122, v123
	v_max3_f32 v92, v92, v121, v140
	v_max3_f32 v93, v93, v142, v143
	v_max3_f32 v92, v92, v141, v124
	v_max3_f32 v93, v93, v126, v127
	v_max3_f32 v92, v92, v125, v93
	v_mov_b32_e32 v93, v92
	s_nop 1
	v_permlane32_swap_b32_e32 v92, v93
	v_max_f32_e32 v92, v92, v93
	v_cmp_lt_f32_e32 vcc, s41, v92
	s_cmp_lg_u64 vcc, 0
	s_cselect_b64 s[36:37], -1, 0
	s_cbranch_vccnz .LBB0_1340
.LBB0_1333:
	s_waitcnt lgkmcnt(14)
	v_mfma_f32_32x32x16_bf16 v[48:63], v[164:167], v[208:211], v[48:63]
	v_exp_f32_e32 v128, v128
	v_exp_f32_e32 v129, v129
	ds_read_b64_tr_b16 v[92:93], v243 offset:32768
	ds_read_b64_tr_b16 v[94:95], v243 offset:33280
	s_waitcnt lgkmcnt(14)
	v_mfma_f32_32x32x16_bf16 v[32:47], v[164:167], v[96:99], v[32:47]
	v_exp_f32_e32 v130, v130
	v_exp_f32_e32 v131, v131
	ds_read_b64_tr_b16 v[96:97], v243 offset:36864
	ds_read_b64_tr_b16 v[98:99], v243 offset:37376
	s_waitcnt lgkmcnt(14)
	v_mfma_f32_32x32x16_bf16 v[48:63], v[156:159], v[100:103], v[48:63]
	v_exp_f32_e32 v132, v132
	v_exp_f32_e32 v133, v133
	ds_read_b64_tr_b16 v[100:101], v243 offset:33792
	ds_read_b64_tr_b16 v[102:103], v243 offset:34304
	s_waitcnt lgkmcnt(14)
	v_mfma_f32_32x32x16_bf16 v[32:47], v[156:159], v[104:107], v[32:47]
	v_exp_f32_e32 v134, v134
	v_exp_f32_e32 v135, v135
	ds_read_b64_tr_b16 v[104:105], v243 offset:37888
	ds_read_b64_tr_b16 v[106:107], v243 offset:38400
	s_waitcnt lgkmcnt(14)
	v_mfma_f32_32x32x16_bf16 v[48:63], v[148:151], v[108:111], v[48:63]
	v_exp_f32_e32 v136, v136
	v_exp_f32_e32 v137, v137
	ds_read_b64_tr_b16 v[108:109], v243 offset:34816
	ds_read_b64_tr_b16 v[110:111], v243 offset:35328
	s_waitcnt lgkmcnt(14)
	v_mfma_f32_32x32x16_bf16 v[32:47], v[148:151], v[80:83], v[32:47]
	v_exp_f32_e32 v138, v138
	v_exp_f32_e32 v139, v139
	ds_read_b64_tr_b16 v[196:197], v243 offset:38912
	ds_read_b64_tr_b16 v[198:199], v243 offset:39424
	s_waitcnt lgkmcnt(14)
	v_mfma_f32_32x32x16_bf16 v[48:63], v[144:147], v[84:87], v[48:63]
	v_exp_f32_e32 v140, v140
	v_exp_f32_e32 v141, v141
	ds_read_b64_tr_b16 v[84:85], v243 offset:35840
	ds_read_b64_tr_b16 v[86:87], v243 offset:36352
	s_waitcnt lgkmcnt(14)
	v_mfma_f32_32x32x16_bf16 v[32:47], v[144:147], v[88:91], v[32:47]
	v_exp_f32_e32 v142, v142
	v_exp_f32_e32 v143, v143
	ds_read_b64_tr_b16 v[88:89], v243 offset:39936
	ds_read_b64_tr_b16 v[90:91], v243 offset:40448
	s_waitcnt lgkmcnt(14)
	v_mfma_f32_32x32x16_bf16 v[16:31], v[164:167], v[92:95], v[16:31]
	v_exp_f32_e32 v112, v112
	v_exp_f32_e32 v113, v113
	s_waitcnt lgkmcnt(12)
	v_mfma_f32_32x32x16_bf16 v[0:15], v[164:167], v[96:99], v[0:15]
	v_exp_f32_e32 v114, v114
	v_exp_f32_e32 v115, v115
	v_add_u32_e32 v92, s38, v238
	ds_read_b128 v[80:83], v92
	ds_read_b128 v[204:207], v92 offset:512
	s_waitcnt lgkmcnt(12)
	v_mfma_f32_32x32x16_bf16 v[16:31], v[156:159], v[100:103], v[16:31]
	v_exp_f32_e32 v116, v116
	v_exp_f32_e32 v117, v117
	ds_read_b128 v[200:203], v92 offset:2048
	ds_read_b128 v[192:195], v92 offset:2560
	s_waitcnt lgkmcnt(12)
	v_mfma_f32_32x32x16_bf16 v[0:15], v[156:159], v[104:107], v[0:15]
	v_exp_f32_e32 v118, v118
	v_exp_f32_e32 v119, v119
	ds_read_b128 v[188:191], v92 offset:4096
	ds_read_b128 v[184:187], v92 offset:4608
	s_waitcnt lgkmcnt(12)
	v_mfma_f32_32x32x16_bf16 v[16:31], v[148:151], v[108:111], v[16:31]
	v_exp_f32_e32 v120, v120
	v_exp_f32_e32 v121, v121
	ds_read_b128 v[180:183], v92 offset:6144
	ds_read_b128 v[176:179], v92 offset:6656
	s_waitcnt lgkmcnt(12)
	v_mfma_f32_32x32x16_bf16 v[0:15], v[148:151], v[196:199], v[0:15]
	v_exp_f32_e32 v122, v122
	v_exp_f32_e32 v123, v123
	s_waitcnt lgkmcnt(10)
	v_mfma_f32_32x32x16_bf16 v[16:31], v[144:147], v[84:87], v[16:31]
	v_exp_f32_e32 v124, v124
	v_exp_f32_e32 v125, v125
	s_waitcnt lgkmcnt(8)
	v_mfma_f32_32x32x16_bf16 v[0:15], v[144:147], v[88:91], v[0:15]
	v_exp_f32_e32 v126, v126
	v_exp_f32_e32 v127, v127
	s_add_i32 s4, s38, 0x2000
	s_cmpk_lg_i32 s38, 0x4000
	s_cselect_b32 s78, s4, 0
	s_waitcnt vmcnt(3) lgkmcnt(0)
	s_barrier
	s_andn2_b64 vcc, exec, s[36:37]
	v_add_u32_e32 v208, s75, v240
	s_cbranch_vccnz .LBB0_1335
	s_waitcnt lgkmcnt(0)
	ds_read_b128 v[84:87], v208 offset:96
	ds_read_b128 v[88:91], v208 offset:64
	ds_read_b128 v[92:95], v208 offset:32
	ds_read_b128 v[96:99], v208
	s_waitcnt lgkmcnt(3)
	v_pk_mul_f32 v[60:61], v[60:61], v[84:85]
	s_waitcnt lgkmcnt(2)
	v_pk_mul_f32 v[56:57], v[56:57], v[88:89]
	s_waitcnt lgkmcnt(1)
	v_pk_mul_f32 v[52:53], v[52:53], v[92:93]
	v_pk_mul_f32 v[62:63], v[62:63], v[86:87]
	v_pk_mul_f32 v[58:59], v[58:59], v[90:91]
	v_pk_mul_f32 v[54:55], v[54:55], v[94:95]
	s_waitcnt lgkmcnt(0)
	v_pk_mul_f32 v[50:51], v[50:51], v[98:99]
	v_pk_mul_f32 v[48:49], v[48:49], v[96:97]
	v_pk_mul_f32 v[44:45], v[44:45], v[84:85]
	v_pk_mul_f32 v[40:41], v[40:41], v[88:89]
	v_pk_mul_f32 v[36:37], v[36:37], v[92:93]
	v_pk_mul_f32 v[46:47], v[46:47], v[86:87]
	v_pk_mul_f32 v[42:43], v[42:43], v[90:91]
	v_pk_mul_f32 v[38:39], v[38:39], v[94:95]
	v_pk_mul_f32 v[34:35], v[34:35], v[98:99]
	v_pk_mul_f32 v[32:33], v[32:33], v[96:97]
	v_pk_mul_f32 v[28:29], v[28:29], v[84:85]
	v_pk_mul_f32 v[24:25], v[24:25], v[88:89]
	v_pk_mul_f32 v[20:21], v[20:21], v[92:93]
	v_pk_mul_f32 v[30:31], v[30:31], v[86:87]
	v_pk_mul_f32 v[26:27], v[26:27], v[90:91]
	v_pk_mul_f32 v[22:23], v[22:23], v[94:95]
	v_pk_mul_f32 v[18:19], v[18:19], v[98:99]
	v_pk_mul_f32 v[16:17], v[16:17], v[96:97]
	v_pk_mul_f32 v[12:13], v[12:13], v[84:85]
	v_pk_mul_f32 v[8:9], v[8:9], v[88:89]
	v_pk_mul_f32 v[4:5], v[4:5], v[92:93]
	v_pk_mul_f32 v[14:15], v[14:15], v[86:87]
	v_pk_mul_f32 v[10:11], v[10:11], v[90:91]
	v_pk_mul_f32 v[6:7], v[6:7], v[94:95]
	v_pk_mul_f32 v[2:3], v[2:3], v[98:99]
	v_pk_mul_f32 v[0:1], v[0:1], v[96:97]
.LBB0_1335:
	s_lshl_b32 s4, s11, 1
	v_add_u32_e32 v209, s4, v239
	ds_read_b64_tr_b16 v[196:197], v209 offset:24576
	ds_read_b64_tr_b16 v[198:199], v209 offset:25088
	s_waitcnt lgkmcnt(9)
	v_mfma_f32_32x32x16_bf16 v[96:111], v[80:83], v[172:175], v[64:79]
	v_add_f32_e32 v84, v128, v129
	v_add_f32_e32 v84, v130, v84
	v_add_f32_e32 v84, v131, v84
	v_add_f32_e32 v84, v132, v84
	v_add_f32_e32 v84, v133, v84
	v_cvt_pk_bf16_f32 v164, v128, v129
	v_cvt_pk_bf16_f32 v165, v130, v131
	ds_read_b64_tr_b16 v[128:129], v209 offset:28672
	ds_read_b64_tr_b16 v[130:131], v209 offset:29184
	v_add_f32_e32 v80, v134, v84
	v_add_f32_e32 v80, v135, v80
	v_add_f32_e32 v80, v136, v80
	v_add_f32_e32 v144, v137, v80
	s_waitcnt lgkmcnt(10)
	v_mfma_f32_32x32x16_bf16 v[80:95], v[204:207], v[172:175], v[64:79]
	v_cvt_pk_bf16_f32 v166, v132, v133
	v_cvt_pk_bf16_f32 v167, v134, v135
	ds_read_b64_tr_b16 v[132:133], v209 offset:25600
	ds_read_b64_tr_b16 v[134:135], v209 offset:26112
	s_waitcnt lgkmcnt(11)
	v_mfma_f32_32x32x16_bf16 v[96:111], v[200:203], v[168:171], v[96:111]
	v_add_f32_e32 v144, v138, v144
	v_add_f32_e32 v144, v139, v144
	v_add_f32_e32 v144, v140, v144
	v_add_f32_e32 v144, v141, v144
	v_cvt_pk_bf16_f32 v156, v136, v137
	v_cvt_pk_bf16_f32 v157, v138, v139
	ds_read_b64_tr_b16 v[136:137], v209 offset:29696
	ds_read_b64_tr_b16 v[138:139], v209 offset:30208
	s_waitcnt lgkmcnt(12)
	v_mfma_f32_32x32x16_bf16 v[80:95], v[192:195], v[168:171], v[80:95]
	v_add_f32_e32 v144, v142, v144
	v_add_f32_e32 v144, v143, v144
	v_add_f32_e32 v144, v112, v144
	v_add_f32_e32 v144, v113, v144
	v_cvt_pk_bf16_f32 v158, v140, v141
	v_cvt_pk_bf16_f32 v159, v142, v143
	ds_read_b64_tr_b16 v[140:141], v209 offset:26624
	ds_read_b64_tr_b16 v[142:143], v209 offset:27136
	s_waitcnt lgkmcnt(13)
	v_mfma_f32_32x32x16_bf16 v[96:111], v[188:191], v[160:163], v[96:111]
	v_add_f32_e32 v144, v114, v144
	v_add_f32_e32 v144, v115, v144
	v_add_f32_e32 v144, v116, v144
	v_add_f32_e32 v144, v117, v144
	v_cvt_pk_bf16_f32 v148, v112, v113
	v_cvt_pk_bf16_f32 v149, v114, v115
	ds_read_b64_tr_b16 v[112:113], v209 offset:30720
	ds_read_b64_tr_b16 v[114:115], v209 offset:31232
	s_waitcnt lgkmcnt(14)
	v_mfma_f32_32x32x16_bf16 v[80:95], v[184:187], v[160:163], v[80:95]
	v_add_f32_e32 v144, v118, v144
	v_add_f32_e32 v144, v119, v144
	v_add_f32_e32 v144, v120, v144
	v_add_f32_e32 v144, v121, v144
	v_cvt_pk_bf16_f32 v150, v116, v117
	v_cvt_pk_bf16_f32 v151, v118, v119
	ds_read_b64_tr_b16 v[116:117], v209 offset:27648
	ds_read_b64_tr_b16 v[118:119], v209 offset:28160
	s_waitcnt lgkmcnt(14)
	v_mfma_f32_32x32x16_bf16 v[96:111], v[180:183], v[152:155], v[96:111]
	v_add_f32_e32 v144, v122, v144
	v_add_f32_e32 v144, v123, v144
	v_add_f32_e32 v144, v124, v144
	v_add_f32_e32 v184, v125, v144
	v_cvt_pk_bf16_f32 v144, v120, v121
	v_cvt_pk_bf16_f32 v145, v122, v123
	ds_read_b64_tr_b16 v[120:121], v209 offset:31744
	ds_read_b64_tr_b16 v[122:123], v209 offset:32256
	v_mfma_f32_32x32x16_bf16 v[80:95], v[176:179], v[152:155], v[80:95]
	v_add_f32_e32 v146, v126, v184
	v_add_f32_e32 v146, v127, v146
	v_add_f32_e32 v241, v241, v146
	v_cvt_pk_bf16_f32 v146, v124, v125
	v_cvt_pk_bf16_f32 v147, v126, v127
	v_max_f32_e32 v124, v96, v97
	s_nop 3
	s_nop 1
	v_max3_f32 v125, v98, v99, v81
	v_max3_f32 v124, v124, v80, v82
	v_max3_f32 v124, v124, v83, v100
	v_max3_f32 v125, v125, v102, v103
	v_max3_f32 v124, v124, v101, v84
	v_max3_f32 v125, v125, v86, v87
	v_max3_f32 v124, v124, v85, v104
	v_max3_f32 v125, v125, v106, v107
	v_max3_f32 v124, v124, v105, v88
	v_max3_f32 v125, v125, v90, v91
	v_max3_f32 v124, v124, v89, v108
	v_max3_f32 v125, v125, v110, v111
	v_max3_f32 v124, v124, v109, v92
	v_max3_f32 v125, v125, v94, v95
	v_max3_f32 v124, v124, v93, v125
	v_mov_b32_e32 v125, v124
	s_add_i32 s4, s38, s76
	s_nop 0
	v_permlane32_swap_b32_e32 v124, v125
	s_mov_b32 m0, s4
	s_nop 0
	global_load_lds_dwordx4 v249, s[98:99]
	s_lshl_b32 s4, s78, 1
	s_add_i32 s4, s4, s77
	s_mov_b32 m0, s4
	s_nop 0
	global_load_lds_dwordx4 v251, s[100:101]
	v_max_f32_e32 v124, v124, v125
	s_addk_i32 s4, 0x2000
	s_mov_b32 m0, s4
	s_nop 0
	global_load_lds_dwordx4 v253, s[100:101]
	v_cmp_lt_f32_e32 vcc, s41, v124
	s_cmp_lg_u64 vcc, 0
	s_cselect_b64 s[36:37], -1, 0
	s_cbranch_vccnz .LBB0_1343
.LBB0_1336:
	s_waitcnt lgkmcnt(14)
	v_mfma_f32_32x32x16_bf16 v[48:63], v[164:167], v[196:199], v[48:63]
	v_exp_f32_e32 v96, v96
	v_exp_f32_e32 v97, v97
	ds_read_b64_tr_b16 v[124:125], v209 offset:32768
	ds_read_b64_tr_b16 v[126:127], v209 offset:33280
	s_waitcnt lgkmcnt(14)
	v_mfma_f32_32x32x16_bf16 v[32:47], v[164:167], v[128:131], v[32:47]
	v_exp_f32_e32 v98, v98
	v_exp_f32_e32 v99, v99
	ds_read_b64_tr_b16 v[128:129], v209 offset:36864
	ds_read_b64_tr_b16 v[130:131], v209 offset:37376
	s_waitcnt lgkmcnt(14)
	v_mfma_f32_32x32x16_bf16 v[48:63], v[156:159], v[132:135], v[48:63]
	v_exp_f32_e32 v100, v100
	v_exp_f32_e32 v101, v101
	ds_read_b64_tr_b16 v[132:133], v209 offset:33792
	ds_read_b64_tr_b16 v[134:135], v209 offset:34304
	s_waitcnt lgkmcnt(14)
	v_mfma_f32_32x32x16_bf16 v[32:47], v[156:159], v[136:139], v[32:47]
	v_exp_f32_e32 v102, v102
	v_exp_f32_e32 v103, v103
	ds_read_b64_tr_b16 v[136:137], v209 offset:37888
	ds_read_b64_tr_b16 v[138:139], v209 offset:38400
	s_waitcnt lgkmcnt(14)
	v_mfma_f32_32x32x16_bf16 v[48:63], v[148:151], v[140:143], v[48:63]
	v_exp_f32_e32 v104, v104
	v_exp_f32_e32 v105, v105
	ds_read_b64_tr_b16 v[140:141], v209 offset:34816
	ds_read_b64_tr_b16 v[142:143], v209 offset:35328
	s_waitcnt lgkmcnt(14)
	v_mfma_f32_32x32x16_bf16 v[32:47], v[148:151], v[112:115], v[32:47]
	v_exp_f32_e32 v106, v106
	v_exp_f32_e32 v107, v107
	ds_read_b64_tr_b16 v[112:113], v209 offset:38912
	ds_read_b64_tr_b16 v[114:115], v209 offset:39424
	s_waitcnt lgkmcnt(14)
	v_mfma_f32_32x32x16_bf16 v[48:63], v[144:147], v[116:119], v[48:63]
	v_exp_f32_e32 v108, v108
	v_exp_f32_e32 v109, v109
	ds_read_b64_tr_b16 v[116:117], v209 offset:35840
	ds_read_b64_tr_b16 v[118:119], v209 offset:36352
	s_waitcnt lgkmcnt(14)
	v_mfma_f32_32x32x16_bf16 v[32:47], v[144:147], v[120:123], v[32:47]
	v_exp_f32_e32 v110, v110
	v_exp_f32_e32 v111, v111
	ds_read_b64_tr_b16 v[120:121], v209 offset:39936
	ds_read_b64_tr_b16 v[122:123], v209 offset:40448
	s_waitcnt lgkmcnt(14)
	v_mfma_f32_32x32x16_bf16 v[16:31], v[164:167], v[124:127], v[16:31]
	v_exp_f32_e32 v80, v80
	v_exp_f32_e32 v81, v81
	s_waitcnt lgkmcnt(12)
	v_mfma_f32_32x32x16_bf16 v[0:15], v[164:167], v[128:131], v[0:15]
	v_exp_f32_e32 v82, v82
	v_exp_f32_e32 v83, v83
	v_add_u32_e32 v124, s78, v238
	ds_read_b128 v[204:207], v124
	ds_read_b128 v[200:203], v124 offset:512
	s_waitcnt lgkmcnt(12)
	v_mfma_f32_32x32x16_bf16 v[16:31], v[156:159], v[132:135], v[16:31]
	v_exp_f32_e32 v84, v84
	v_exp_f32_e32 v85, v85
	ds_read_b128 v[196:199], v124 offset:2048
	ds_read_b128 v[192:195], v124 offset:2560
	s_waitcnt lgkmcnt(12)
	v_mfma_f32_32x32x16_bf16 v[0:15], v[156:159], v[136:139], v[0:15]
	v_exp_f32_e32 v86, v86
	v_exp_f32_e32 v87, v87
	ds_read_b128 v[188:191], v124 offset:4096
	ds_read_b128 v[184:187], v124 offset:4608
	s_waitcnt lgkmcnt(12)
	v_mfma_f32_32x32x16_bf16 v[16:31], v[148:151], v[140:143], v[16:31]
	v_exp_f32_e32 v88, v88
	v_exp_f32_e32 v89, v89
	ds_read_b128 v[180:183], v124 offset:6144
	ds_read_b128 v[176:179], v124 offset:6656
	s_waitcnt lgkmcnt(12)
	v_mfma_f32_32x32x16_bf16 v[0:15], v[148:151], v[112:115], v[0:15]
	v_exp_f32_e32 v90, v90
	v_exp_f32_e32 v91, v91
	s_waitcnt lgkmcnt(10)
	v_mfma_f32_32x32x16_bf16 v[16:31], v[144:147], v[116:119], v[16:31]
	v_exp_f32_e32 v92, v92
	v_exp_f32_e32 v93, v93
	s_waitcnt lgkmcnt(8)
	v_mfma_f32_32x32x16_bf16 v[0:15], v[144:147], v[120:123], v[0:15]
	v_exp_f32_e32 v94, v94
	v_exp_f32_e32 v95, v95
	s_add_i32 s10, s10, 2
	s_add_i32 s4, s78, 0x2000
	s_cmpk_lg_i32 s78, 0x4000
	s_cselect_b32 s79, s4, 0
	s_add_u32 s98, s98, s16
	s_addc_u32 s99, s99, s17
	s_add_u32 s100, s100, s16
	s_addc_u32 s101, s101, s17
	s_waitcnt vmcnt(3) lgkmcnt(0)
	s_barrier
	s_andn2_b64 vcc, exec, s[36:37]
	s_cbranch_vccnz .LBB0_1338
	s_waitcnt lgkmcnt(0)
	ds_read_b128 v[112:115], v208 offset:96
	ds_read_b128 v[116:119], v208 offset:64
	ds_read_b128 v[120:123], v208 offset:32
	ds_read_b128 v[124:127], v208
	s_waitcnt lgkmcnt(3)
	v_pk_mul_f32 v[60:61], v[60:61], v[112:113]
	s_waitcnt lgkmcnt(2)
	v_pk_mul_f32 v[56:57], v[56:57], v[116:117]
	s_waitcnt lgkmcnt(1)
	v_pk_mul_f32 v[52:53], v[52:53], v[120:121]
	v_pk_mul_f32 v[62:63], v[62:63], v[114:115]
	v_pk_mul_f32 v[58:59], v[58:59], v[118:119]
	v_pk_mul_f32 v[54:55], v[54:55], v[122:123]
	s_waitcnt lgkmcnt(0)
	v_pk_mul_f32 v[50:51], v[50:51], v[126:127]
	v_pk_mul_f32 v[48:49], v[48:49], v[124:125]
	v_pk_mul_f32 v[44:45], v[44:45], v[112:113]
	v_pk_mul_f32 v[40:41], v[40:41], v[116:117]
	v_pk_mul_f32 v[36:37], v[36:37], v[120:121]
	v_pk_mul_f32 v[46:47], v[46:47], v[114:115]
	v_pk_mul_f32 v[42:43], v[42:43], v[118:119]
	v_pk_mul_f32 v[38:39], v[38:39], v[122:123]
	v_pk_mul_f32 v[34:35], v[34:35], v[126:127]
	v_pk_mul_f32 v[32:33], v[32:33], v[124:125]
	v_pk_mul_f32 v[28:29], v[28:29], v[112:113]
	v_pk_mul_f32 v[24:25], v[24:25], v[116:117]
	v_pk_mul_f32 v[20:21], v[20:21], v[120:121]
	v_pk_mul_f32 v[30:31], v[30:31], v[114:115]
	v_pk_mul_f32 v[26:27], v[26:27], v[118:119]
	v_pk_mul_f32 v[22:23], v[22:23], v[122:123]
	v_pk_mul_f32 v[18:19], v[18:19], v[126:127]
	v_pk_mul_f32 v[16:17], v[16:17], v[124:125]
	v_pk_mul_f32 v[12:13], v[12:13], v[112:113]
	v_pk_mul_f32 v[8:9], v[8:9], v[116:117]
	v_pk_mul_f32 v[4:5], v[4:5], v[120:121]
	v_pk_mul_f32 v[14:15], v[14:15], v[114:115]
	v_pk_mul_f32 v[10:11], v[10:11], v[118:119]
	v_pk_mul_f32 v[6:7], v[6:7], v[122:123]
	v_pk_mul_f32 v[2:3], v[2:3], v[126:127]
	v_pk_mul_f32 v[0:1], v[0:1], v[124:125]
.LBB0_1338:
	s_cmp_ge_i32 s10, s70
	s_cbranch_scc1 .LBB0_1347
	s_mov_b32 s4, s38
	s_mov_b32 s11, s78
	s_mov_b32 s38, s79
	s_branch .LBB0_1332

.LBB0_1360:
	s_waitcnt lgkmcnt(14)
	v_mfma_f32_32x32x16_bf16 v[48:63], v[160:163], v[208:211], v[48:63]
	v_exp_f32_e32 v128, v128
	v_exp_f32_e32 v129, v129
	ds_read_b64_tr_b16 v[92:93], v245 offset:32768
	ds_read_b64_tr_b16 v[94:95], v245 offset:33280
	s_waitcnt lgkmcnt(14)
	v_mfma_f32_32x32x16_bf16 v[32:47], v[160:163], v[96:99], v[32:47]
	v_exp_f32_e32 v130, v130
	v_exp_f32_e32 v131, v131
	ds_read_b64_tr_b16 v[96:97], v245 offset:36864
	ds_read_b64_tr_b16 v[98:99], v245 offset:37376
	s_waitcnt lgkmcnt(14)
	v_mfma_f32_32x32x16_bf16 v[48:63], v[156:159], v[100:103], v[48:63]
	v_exp_f32_e32 v132, v132
	v_exp_f32_e32 v133, v133
	ds_read_b64_tr_b16 v[100:101], v245 offset:33792
	ds_read_b64_tr_b16 v[102:103], v245 offset:34304
	s_waitcnt lgkmcnt(14)
	v_mfma_f32_32x32x16_bf16 v[32:47], v[156:159], v[104:107], v[32:47]
	v_exp_f32_e32 v134, v134
	v_exp_f32_e32 v135, v135
	ds_read_b64_tr_b16 v[104:105], v245 offset:37888
	ds_read_b64_tr_b16 v[106:107], v245 offset:38400
	s_waitcnt lgkmcnt(14)
	v_mfma_f32_32x32x16_bf16 v[48:63], v[148:151], v[108:111], v[48:63]
	v_exp_f32_e32 v136, v136
	v_exp_f32_e32 v137, v137
	ds_read_b64_tr_b16 v[108:109], v245 offset:34816
	ds_read_b64_tr_b16 v[110:111], v245 offset:35328
	s_waitcnt lgkmcnt(14)
	v_mfma_f32_32x32x16_bf16 v[32:47], v[148:151], v[80:83], v[32:47]
	v_exp_f32_e32 v138, v138
	v_exp_f32_e32 v139, v139
	ds_read_b64_tr_b16 v[196:197], v245 offset:38912
	ds_read_b64_tr_b16 v[198:199], v245 offset:39424
	s_waitcnt lgkmcnt(14)
	v_mfma_f32_32x32x16_bf16 v[48:63], v[144:147], v[84:87], v[48:63]
	v_exp_f32_e32 v140, v140
	v_exp_f32_e32 v141, v141
	ds_read_b64_tr_b16 v[84:85], v245 offset:35840
	ds_read_b64_tr_b16 v[86:87], v245 offset:36352
	s_waitcnt lgkmcnt(14)
	v_mfma_f32_32x32x16_bf16 v[32:47], v[144:147], v[88:91], v[32:47]
	v_exp_f32_e32 v142, v142
	v_exp_f32_e32 v143, v143
	ds_read_b64_tr_b16 v[88:89], v245 offset:39936
	ds_read_b64_tr_b16 v[90:91], v245 offset:40448
	s_waitcnt lgkmcnt(14)
	v_mfma_f32_32x32x16_bf16 v[16:31], v[160:163], v[92:95], v[16:31]
	v_exp_f32_e32 v112, v112
	v_exp_f32_e32 v113, v113
	s_waitcnt lgkmcnt(12)
	v_mfma_f32_32x32x16_bf16 v[0:15], v[160:163], v[96:99], v[0:15]
	v_exp_f32_e32 v114, v114
	v_exp_f32_e32 v115, v115
	v_add_u32_e32 v92, s36, v239
	ds_read_b128 v[80:83], v92
	ds_read_b128 v[204:207], v92 offset:512
	s_waitcnt lgkmcnt(12)
	v_mfma_f32_32x32x16_bf16 v[16:31], v[156:159], v[100:103], v[16:31]
	v_exp_f32_e32 v116, v116
	v_exp_f32_e32 v117, v117
	ds_read_b128 v[200:203], v92 offset:2048
	ds_read_b128 v[192:195], v92 offset:2560
	s_waitcnt lgkmcnt(12)
	v_mfma_f32_32x32x16_bf16 v[0:15], v[156:159], v[104:107], v[0:15]
	v_exp_f32_e32 v118, v118
	v_exp_f32_e32 v119, v119
	ds_read_b128 v[188:191], v92 offset:4096
	ds_read_b128 v[184:187], v92 offset:4608
	s_waitcnt lgkmcnt(12)
	v_mfma_f32_32x32x16_bf16 v[16:31], v[148:151], v[108:111], v[16:31]
	v_exp_f32_e32 v120, v120
	v_exp_f32_e32 v121, v121
	ds_read_b128 v[180:183], v92 offset:6144
	ds_read_b128 v[176:179], v92 offset:6656
	s_waitcnt lgkmcnt(12)
	v_mfma_f32_32x32x16_bf16 v[0:15], v[148:151], v[196:199], v[0:15]
	v_exp_f32_e32 v122, v122
	v_exp_f32_e32 v123, v123
	s_waitcnt lgkmcnt(10)
	v_mfma_f32_32x32x16_bf16 v[16:31], v[144:147], v[84:87], v[16:31]
	v_exp_f32_e32 v124, v124
	v_exp_f32_e32 v125, v125
	s_waitcnt lgkmcnt(8)
	v_mfma_f32_32x32x16_bf16 v[0:15], v[144:147], v[88:91], v[0:15]
	v_exp_f32_e32 v126, v126
	v_exp_f32_e32 v127, v127
	s_add_i32 s4, s36, 0x2000
	s_cmpk_lg_i32 s36, 0x4000
	s_cselect_b32 s75, s4, 0
	s_waitcnt vmcnt(3) lgkmcnt(0)
	s_barrier
	s_andn2_b64 vcc, exec, s[10:11]
	v_add_u32_e32 v208, s49, v242
	s_cbranch_vccnz .LBB0_1362
	s_waitcnt lgkmcnt(0)
	ds_read_b128 v[84:87], v208 offset:96
	ds_read_b128 v[88:91], v208 offset:64
	ds_read_b128 v[92:95], v208 offset:32
	ds_read_b128 v[96:99], v208
	s_waitcnt lgkmcnt(3)
	v_pk_mul_f32 v[60:61], v[60:61], v[84:85]
	s_waitcnt lgkmcnt(2)
	v_pk_mul_f32 v[56:57], v[56:57], v[88:89]
	s_waitcnt lgkmcnt(1)
	v_pk_mul_f32 v[52:53], v[52:53], v[92:93]
	v_pk_mul_f32 v[62:63], v[62:63], v[86:87]
	v_pk_mul_f32 v[58:59], v[58:59], v[90:91]
	v_pk_mul_f32 v[54:55], v[54:55], v[94:95]
	s_waitcnt lgkmcnt(0)
	v_pk_mul_f32 v[50:51], v[50:51], v[98:99]
	v_pk_mul_f32 v[48:49], v[48:49], v[96:97]
	v_pk_mul_f32 v[44:45], v[44:45], v[84:85]
	v_pk_mul_f32 v[40:41], v[40:41], v[88:89]
	v_pk_mul_f32 v[36:37], v[36:37], v[92:93]
	v_pk_mul_f32 v[46:47], v[46:47], v[86:87]
	v_pk_mul_f32 v[42:43], v[42:43], v[90:91]
	v_pk_mul_f32 v[38:39], v[38:39], v[94:95]
	v_pk_mul_f32 v[34:35], v[34:35], v[98:99]
	v_pk_mul_f32 v[32:33], v[32:33], v[96:97]
	v_pk_mul_f32 v[28:29], v[28:29], v[84:85]
	v_pk_mul_f32 v[24:25], v[24:25], v[88:89]
	v_pk_mul_f32 v[20:21], v[20:21], v[92:93]
	v_pk_mul_f32 v[30:31], v[30:31], v[86:87]
	v_pk_mul_f32 v[26:27], v[26:27], v[90:91]
	v_pk_mul_f32 v[22:23], v[22:23], v[94:95]
	v_pk_mul_f32 v[18:19], v[18:19], v[98:99]
	v_pk_mul_f32 v[16:17], v[16:17], v[96:97]
	v_pk_mul_f32 v[12:13], v[12:13], v[84:85]
	v_pk_mul_f32 v[8:9], v[8:9], v[88:89]
	v_pk_mul_f32 v[4:5], v[4:5], v[92:93]
	v_pk_mul_f32 v[14:15], v[14:15], v[86:87]
	v_pk_mul_f32 v[10:11], v[10:11], v[90:91]
	v_pk_mul_f32 v[6:7], v[6:7], v[94:95]
	v_pk_mul_f32 v[2:3], v[2:3], v[98:99]
	v_pk_mul_f32 v[0:1], v[0:1], v[96:97]
.LBB0_1362:
	s_lshl_b32 s4, s35, 1
	v_add_u32_e32 v209, s4, v240
	ds_read_b64_tr_b16 v[196:197], v209 offset:24576
	ds_read_b64_tr_b16 v[198:199], v209 offset:25088
	s_waitcnt lgkmcnt(9)
	v_mfma_f32_32x32x16_bf16 v[96:111], v[80:83], v[172:175], v[64:79]
	v_add_f32_e32 v84, v128, v129
	v_add_f32_e32 v84, v130, v84
	v_add_f32_e32 v84, v131, v84
	v_add_f32_e32 v84, v132, v84
	v_add_f32_e32 v84, v133, v84
	v_cvt_pk_bf16_f32 v160, v128, v129
	v_cvt_pk_bf16_f32 v161, v130, v131
	ds_read_b64_tr_b16 v[128:129], v209 offset:28672
	ds_read_b64_tr_b16 v[130:131], v209 offset:29184
	v_add_f32_e32 v80, v134, v84
	v_add_f32_e32 v80, v135, v80
	v_add_f32_e32 v80, v136, v80
	v_add_f32_e32 v144, v137, v80
	s_waitcnt lgkmcnt(10)
	v_mfma_f32_32x32x16_bf16 v[80:95], v[204:207], v[172:175], v[64:79]
	v_cvt_pk_bf16_f32 v162, v132, v133
	v_cvt_pk_bf16_f32 v163, v134, v135
	ds_read_b64_tr_b16 v[132:133], v209 offset:25600
	ds_read_b64_tr_b16 v[134:135], v209 offset:26112
	s_waitcnt lgkmcnt(11)
	v_mfma_f32_32x32x16_bf16 v[96:111], v[200:203], v[168:171], v[96:111]
	v_add_f32_e32 v144, v138, v144
	v_add_f32_e32 v144, v139, v144
	v_add_f32_e32 v144, v140, v144
	v_add_f32_e32 v144, v141, v144
	v_cvt_pk_bf16_f32 v156, v136, v137
	v_cvt_pk_bf16_f32 v157, v138, v139
	ds_read_b64_tr_b16 v[136:137], v209 offset:29696
	ds_read_b64_tr_b16 v[138:139], v209 offset:30208
	s_waitcnt lgkmcnt(12)
	v_mfma_f32_32x32x16_bf16 v[80:95], v[192:195], v[168:171], v[80:95]
	v_add_f32_e32 v144, v142, v144
	v_add_f32_e32 v144, v143, v144
	v_add_f32_e32 v144, v112, v144
	v_add_f32_e32 v144, v113, v144
	v_cvt_pk_bf16_f32 v158, v140, v141
	v_cvt_pk_bf16_f32 v159, v142, v143
	ds_read_b64_tr_b16 v[140:141], v209 offset:26624
	ds_read_b64_tr_b16 v[142:143], v209 offset:27136
	s_waitcnt lgkmcnt(13)
	v_mfma_f32_32x32x16_bf16 v[96:111], v[188:191], v[164:167], v[96:111]
	v_add_f32_e32 v144, v114, v144
	v_add_f32_e32 v144, v115, v144
	v_add_f32_e32 v144, v116, v144
	v_add_f32_e32 v144, v117, v144
	v_cvt_pk_bf16_f32 v148, v112, v113
	v_cvt_pk_bf16_f32 v149, v114, v115
	ds_read_b64_tr_b16 v[112:113], v209 offset:30720
	ds_read_b64_tr_b16 v[114:115], v209 offset:31232
	s_waitcnt lgkmcnt(14)
	v_mfma_f32_32x32x16_bf16 v[80:95], v[184:187], v[164:167], v[80:95]
	v_add_f32_e32 v144, v118, v144
	v_add_f32_e32 v144, v119, v144
	v_add_f32_e32 v144, v120, v144
	v_add_f32_e32 v144, v121, v144
	v_cvt_pk_bf16_f32 v150, v116, v117
	v_cvt_pk_bf16_f32 v151, v118, v119
	ds_read_b64_tr_b16 v[116:117], v209 offset:27648
	ds_read_b64_tr_b16 v[118:119], v209 offset:28160
	s_waitcnt lgkmcnt(14)
	v_mfma_f32_32x32x16_bf16 v[96:111], v[180:183], v[152:155], v[96:111]
	v_add_f32_e32 v144, v122, v144
	v_add_f32_e32 v144, v123, v144
	v_add_f32_e32 v144, v124, v144
	v_add_f32_e32 v184, v125, v144
	v_cvt_pk_bf16_f32 v144, v120, v121
	v_cvt_pk_bf16_f32 v145, v122, v123
	ds_read_b64_tr_b16 v[120:121], v209 offset:31744
	ds_read_b64_tr_b16 v[122:123], v209 offset:32256
	v_mfma_f32_32x32x16_bf16 v[80:95], v[176:179], v[152:155], v[80:95]
	v_add_f32_e32 v146, v126, v184
	v_add_f32_e32 v146, v127, v146
	v_add_f32_e32 v180, 0, v146
	v_cvt_pk_bf16_f32 v146, v124, v125
	v_cvt_pk_bf16_f32 v147, v126, v127
	v_max_f32_e32 v124, v96, v97
	s_nop 3
	s_nop 1
	v_max3_f32 v125, v98, v99, v81
	v_max3_f32 v124, v124, v80, v82
	v_max3_f32 v124, v124, v83, v100
	v_max3_f32 v125, v125, v102, v103
	v_max3_f32 v124, v124, v101, v84
	v_max3_f32 v125, v125, v86, v87
	v_max3_f32 v124, v124, v85, v104
	v_max3_f32 v125, v125, v106, v107
	v_max3_f32 v124, v124, v105, v88
	v_max3_f32 v125, v125, v90, v91
	v_max3_f32 v124, v124, v89, v108
	v_max3_f32 v125, v125, v110, v111
	v_max3_f32 v124, v124, v109, v92
	v_max3_f32 v125, v125, v94, v95
	v_max3_f32 v124, v124, v93, v125
	v_mov_b32_e32 v125, v124
	s_add_i32 s4, s36, s71
	s_nop 0
	v_permlane32_swap_b32_e32 v124, v125
	s_mov_b32 m0, s4
	s_nop 0
	global_load_lds_dwordx4 v249, s[98:99]
	s_lshl_b32 s4, s75, 1
	s_add_i32 s4, s4, s74
	s_mov_b32 m0, s4
	s_nop 0
	global_load_lds_dwordx4 v251, s[100:101]
	v_max_f32_e32 v124, v124, v125
	s_addk_i32 s4, 0x2000
	s_mov_b32 m0, s4
	s_nop 0
	global_load_lds_dwordx4 v253, s[100:101]
	v_cmp_lt_f32_e32 vcc, s41, v124
	s_cmp_lg_u64 vcc, 0
	v_add_f32_e32 v243, v233, v180
	s_cselect_b64 s[10:11], -1, 0
	s_cbranch_vccnz .LBB0_1370
.LBB0_1363:
	s_waitcnt lgkmcnt(14)
	v_mfma_f32_32x32x16_bf16 v[48:63], v[160:163], v[196:199], v[48:63]
	v_exp_f32_e32 v96, v96
	v_exp_f32_e32 v97, v97
	ds_read_b64_tr_b16 v[124:125], v209 offset:32768
	ds_read_b64_tr_b16 v[126:127], v209 offset:33280
	s_waitcnt lgkmcnt(14)
	v_mfma_f32_32x32x16_bf16 v[32:47], v[160:163], v[128:131], v[32:47]
	v_exp_f32_e32 v98, v98
	v_exp_f32_e32 v99, v99
	ds_read_b64_tr_b16 v[128:129], v209 offset:36864
	ds_read_b64_tr_b16 v[130:131], v209 offset:37376
	s_waitcnt lgkmcnt(14)
	v_mfma_f32_32x32x16_bf16 v[48:63], v[156:159], v[132:135], v[48:63]
	v_exp_f32_e32 v100, v100
	v_exp_f32_e32 v101, v101
	ds_read_b64_tr_b16 v[132:133], v209 offset:33792
	ds_read_b64_tr_b16 v[134:135], v209 offset:34304
	s_waitcnt lgkmcnt(14)
	v_mfma_f32_32x32x16_bf16 v[32:47], v[156:159], v[136:139], v[32:47]
	v_exp_f32_e32 v102, v102
	v_exp_f32_e32 v103, v103
	ds_read_b64_tr_b16 v[136:137], v209 offset:37888
	ds_read_b64_tr_b16 v[138:139], v209 offset:38400
	s_waitcnt lgkmcnt(14)
	v_mfma_f32_32x32x16_bf16 v[48:63], v[148:151], v[140:143], v[48:63]
	v_exp_f32_e32 v104, v104
	v_exp_f32_e32 v105, v105
	ds_read_b64_tr_b16 v[140:141], v209 offset:34816
	ds_read_b64_tr_b16 v[142:143], v209 offset:35328
	s_waitcnt lgkmcnt(14)
	v_mfma_f32_32x32x16_bf16 v[32:47], v[148:151], v[112:115], v[32:47]
	v_exp_f32_e32 v106, v106
	v_exp_f32_e32 v107, v107
	ds_read_b64_tr_b16 v[112:113], v209 offset:38912
	ds_read_b64_tr_b16 v[114:115], v209 offset:39424
	s_waitcnt lgkmcnt(14)
	v_mfma_f32_32x32x16_bf16 v[48:63], v[144:147], v[116:119], v[48:63]
	v_exp_f32_e32 v108, v108
	v_exp_f32_e32 v109, v109
	ds_read_b64_tr_b16 v[116:117], v209 offset:35840
	ds_read_b64_tr_b16 v[118:119], v209 offset:36352
	s_waitcnt lgkmcnt(14)
	v_mfma_f32_32x32x16_bf16 v[32:47], v[144:147], v[120:123], v[32:47]
	v_exp_f32_e32 v110, v110
	v_exp_f32_e32 v111, v111
	ds_read_b64_tr_b16 v[120:121], v209 offset:39936
	ds_read_b64_tr_b16 v[122:123], v209 offset:40448
	s_waitcnt lgkmcnt(14)
	v_mfma_f32_32x32x16_bf16 v[16:31], v[160:163], v[124:127], v[16:31]
	v_exp_f32_e32 v80, v80
	v_exp_f32_e32 v81, v81
	s_waitcnt lgkmcnt(12)
	v_mfma_f32_32x32x16_bf16 v[0:15], v[160:163], v[128:131], v[0:15]
	v_exp_f32_e32 v82, v82
	v_exp_f32_e32 v83, v83
	v_add_u32_e32 v124, s75, v239
	ds_read_b128 v[204:207], v124
	ds_read_b128 v[200:203], v124 offset:512
	s_waitcnt lgkmcnt(12)
	v_mfma_f32_32x32x16_bf16 v[16:31], v[156:159], v[132:135], v[16:31]
	v_exp_f32_e32 v84, v84
	v_exp_f32_e32 v85, v85
	ds_read_b128 v[196:199], v124 offset:2048
	ds_read_b128 v[192:195], v124 offset:2560
	s_waitcnt lgkmcnt(12)
	v_mfma_f32_32x32x16_bf16 v[0:15], v[156:159], v[136:139], v[0:15]
	v_exp_f32_e32 v86, v86
	v_exp_f32_e32 v87, v87
	ds_read_b128 v[188:191], v124 offset:4096
	ds_read_b128 v[184:187], v124 offset:4608
	s_waitcnt lgkmcnt(12)
	v_mfma_f32_32x32x16_bf16 v[16:31], v[148:151], v[140:143], v[16:31]
	v_exp_f32_e32 v88, v88
	v_exp_f32_e32 v89, v89
	ds_read_b128 v[180:183], v124 offset:6144
	ds_read_b128 v[176:179], v124 offset:6656
	s_waitcnt lgkmcnt(12)
	v_mfma_f32_32x32x16_bf16 v[0:15], v[148:151], v[112:115], v[0:15]
	v_exp_f32_e32 v90, v90
	v_exp_f32_e32 v91, v91
	s_waitcnt lgkmcnt(10)
	v_mfma_f32_32x32x16_bf16 v[16:31], v[144:147], v[116:119], v[16:31]
	v_exp_f32_e32 v92, v92
	v_exp_f32_e32 v93, v93
	s_waitcnt lgkmcnt(8)
	v_mfma_f32_32x32x16_bf16 v[0:15], v[144:147], v[120:123], v[0:15]
	v_exp_f32_e32 v94, v94
	v_exp_f32_e32 v95, v95
	s_add_i32 s34, s34, 2
	s_add_i32 s4, s75, 0x2000
	s_cmpk_lg_i32 s75, 0x4000
	s_cselect_b32 s76, s4, 0
	s_add_u32 s98, s98, s16
	s_addc_u32 s99, s99, s17
	s_add_u32 s100, s100, s16
	s_addc_u32 s101, s101, s17
	s_waitcnt vmcnt(3) lgkmcnt(0)
	s_barrier
	s_andn2_b64 vcc, exec, s[10:11]
	s_cbranch_vccnz .LBB0_1365
	s_waitcnt lgkmcnt(0)
	ds_read_b128 v[112:115], v208 offset:96
	ds_read_b128 v[116:119], v208 offset:64
	ds_read_b128 v[120:123], v208 offset:32
	ds_read_b128 v[124:127], v208
	s_waitcnt lgkmcnt(3)
	v_pk_mul_f32 v[60:61], v[60:61], v[112:113]
	s_waitcnt lgkmcnt(2)
	v_pk_mul_f32 v[56:57], v[56:57], v[116:117]
	s_waitcnt lgkmcnt(1)
	v_pk_mul_f32 v[52:53], v[52:53], v[120:121]
	v_pk_mul_f32 v[62:63], v[62:63], v[114:115]
	v_pk_mul_f32 v[58:59], v[58:59], v[118:119]
	v_pk_mul_f32 v[54:55], v[54:55], v[122:123]
	s_waitcnt lgkmcnt(0)
	v_pk_mul_f32 v[50:51], v[50:51], v[126:127]
	v_pk_mul_f32 v[48:49], v[48:49], v[124:125]
	v_pk_mul_f32 v[44:45], v[44:45], v[112:113]
	v_pk_mul_f32 v[40:41], v[40:41], v[116:117]
	v_pk_mul_f32 v[36:37], v[36:37], v[120:121]
	v_pk_mul_f32 v[46:47], v[46:47], v[114:115]
	v_pk_mul_f32 v[42:43], v[42:43], v[118:119]
	v_pk_mul_f32 v[38:39], v[38:39], v[122:123]
	v_pk_mul_f32 v[34:35], v[34:35], v[126:127]
	v_pk_mul_f32 v[32:33], v[32:33], v[124:125]
	v_pk_mul_f32 v[28:29], v[28:29], v[112:113]
	v_pk_mul_f32 v[24:25], v[24:25], v[116:117]
	v_pk_mul_f32 v[20:21], v[20:21], v[120:121]
	v_pk_mul_f32 v[30:31], v[30:31], v[114:115]
	v_pk_mul_f32 v[26:27], v[26:27], v[118:119]
	v_pk_mul_f32 v[22:23], v[22:23], v[122:123]
	v_pk_mul_f32 v[18:19], v[18:19], v[126:127]
	v_pk_mul_f32 v[16:17], v[16:17], v[124:125]
	v_pk_mul_f32 v[12:13], v[12:13], v[112:113]
	v_pk_mul_f32 v[8:9], v[8:9], v[116:117]
	v_pk_mul_f32 v[4:5], v[4:5], v[120:121]
	v_pk_mul_f32 v[14:15], v[14:15], v[114:115]
	v_pk_mul_f32 v[10:11], v[10:11], v[118:119]
	v_pk_mul_f32 v[6:7], v[6:7], v[122:123]
	v_pk_mul_f32 v[2:3], v[2:3], v[126:127]
	v_pk_mul_f32 v[0:1], v[0:1], v[124:125]
.LBB0_1365:
	s_cmp_ge_i32 s34, s70
	s_cbranch_scc1 .LBB0_1424
	s_mov_b32 s4, s36
	s_mov_b32 s35, s75
	s_mov_b32 s36, s76
	s_branch .LBB0_1359
